# xn (P0 RMSNorm output) stores also written through (sc1)
# baseline (speedup 1.0000x reference)
; __device__ __forceinline__ unsigned cvt_pk_bf16(float lo, float hi) { unsigned r; asm volatile("v_cvt_pk_bf16_f32 %0, %1, %2" : "=v"(r) : "v"(lo), "v"(hi)); return r; }
; __global__ void __launch_bounds__(NWAVES * 64, 2) hymba_fwd(Args a) {
;     ...
;             for (int q = 0; q < 2; ++q) { float t = 0.f;
; #pragma unroll
;                 for (int j = 0; j < 8; ++j) t += (v[q][j].x * v[q][j].x + v[q][j].y * v[q][j].y) + (v[q][j].z * v[q][j].z + v[q][j].w * v[q][j].w);
;                 s[q] = t; }
; #pragma unroll
;             for (int q = 0; q < 2; ++q) { const int mm = m + q * NW2; if (mm >= mEnd) continue;
;                 const float ms = wave_sum(s[q]) * (1.0f / DM) + RMS_EPS; const float r = 1.0f / sqrtf(ms);
;                 if (lane == 0) ((float*)(ws + WS_RX))[mm] = sqrtf(ms);
;                 v4u* o = (v4u*)(R1 + (size_t)mm * DM);
; #pragma unroll
;                 for (int j = 0; j < 4; ++j) { v4u w; w.x = cvt_pk_bf16(v[q][2 * j].x * r, v[q][2 * j].y * r); w.y = cvt_pk_bf16(v[q][2 * j].z * r, v[q][2 * j].w * r);
;                     w.z = cvt_pk_bf16(v[q][2 * j + 1].x * r, v[q][2 * j + 1].y * r); w.w = cvt_pk_bf16(v[q][2 * j + 1].z * r, v[q][2 * j + 1].w * r); o[64 * j + lane] = w; } }
.LBB0_337:
	s_or_b64 exec, exec, s[6:7]
	v_div_scale_f32 v81, s[6:7], v80, v80, 1.0
	v_rcp_f32_e32 v82, v81
	v_div_scale_f32 v83, vcc, 1.0, v80, 1.0
	s_lshl_b64 s[6:7], s[8:9], 12
	v_fma_f32 v84, -v81, v82, 1.0
	v_fmac_f32_e32 v82, v84, v82
	v_mul_f32_e32 v84, v83, v82
	v_fma_f32 v85, -v81, v84, v83
	v_fmac_f32_e32 v84, v85, v82
	v_fma_f32 v81, -v81, v84, v83
	v_div_fmas_f32 v81, v81, v82, v84
	v_div_fixup_f32 v80, v81, v80, 1.0
	v_mul_f32_e32 v62, v80, v62
	v_mul_f32_e32 v63, v80, v63
	v_cvt_pk_bf16_f32 v62, v62, v63
	v_mul_f32_e32 v63, v80, v64
	v_mul_f32_e32 v64, v80, v65
	v_mul_f32_e32 v58, v80, v58
	v_mul_f32_e32 v59, v80, v59
	v_cvt_pk_bf16_f32 v63, v63, v64
	v_cvt_pk_bf16_f32 v64, v58, v59
	v_mul_f32_e32 v58, v80, v60
	v_mul_f32_e32 v59, v80, v61
	v_cvt_pk_bf16_f32 v65, v58, v59
	v_lshl_add_u64 v[58:59], v[68:69], 0, s[6:7]
	v_mul_f32_e32 v54, v80, v54
	v_mul_f32_e32 v55, v80, v55
	global_store_dwordx4 v[58:59], v[62:65], off sc1
	v_cvt_pk_bf16_f32 v54, v54, v55
	v_mul_f32_e32 v55, v80, v56
	v_mul_f32_e32 v56, v80, v57
	v_mul_f32_e32 v50, v80, v50
	v_mul_f32_e32 v51, v80, v51
	v_mul_f32_e32 v46, v80, v46
	v_mul_f32_e32 v47, v80, v47
	v_cvt_pk_bf16_f32 v55, v55, v56
	v_cvt_pk_bf16_f32 v56, v50, v51
	v_mul_f32_e32 v50, v80, v52
	v_mul_f32_e32 v51, v80, v53
	v_cvt_pk_bf16_f32 v57, v50, v51
	global_store_dwordx4 v[58:59], v[54:57], off offset:1024 sc1
	v_cvt_pk_bf16_f32 v46, v46, v47
	v_mul_f32_e32 v47, v80, v48
	v_mul_f32_e32 v48, v80, v49
	v_mul_f32_e32 v42, v80, v42
	v_mul_f32_e32 v43, v80, v43
	v_mul_f32_e32 v38, v80, v38
	v_mul_f32_e32 v39, v80, v39
	v_cvt_pk_bf16_f32 v47, v47, v48
	v_cvt_pk_bf16_f32 v48, v42, v43
	v_mul_f32_e32 v42, v80, v44
	v_mul_f32_e32 v43, v80, v45
	v_cvt_pk_bf16_f32 v49, v42, v43
	global_store_dwordx4 v[58:59], v[46:49], off offset:2048 sc1
	v_cvt_pk_bf16_f32 v38, v38, v39
	v_mul_f32_e32 v39, v80, v40
	v_mul_f32_e32 v40, v80, v41
	v_mul_f32_e32 v34, v80, v34
	v_mul_f32_e32 v35, v80, v35
	s_andn2_b64 vcc, exec, s[14:15]
	v_cvt_pk_bf16_f32 v39, v39, v40
	v_cvt_pk_bf16_f32 v40, v34, v35
	v_mul_f32_e32 v34, v80, v36
	v_mul_f32_e32 v35, v80, v37
	v_cvt_pk_bf16_f32 v41, v34, v35
	global_store_dwordx4 v[58:59], v[38:41], off offset:3072 sc1
	s_cbranch_vccnz .LBB0_334
	s_waitcnt vmcnt(10)
	v_mul_f32_e32 v34, v31, v31
	v_mul_f32_e32 v35, v33, v33
	v_fmac_f32_e32 v34, v30, v30
	v_fmac_f32_e32 v35, v32, v32
	v_add_f32_e32 v34, v34, v35
	v_mul_f32_e32 v35, v27, v27
	v_mul_f32_e32 v36, v29, v29
	v_fmac_f32_e32 v35, v26, v26
	v_fmac_f32_e32 v36, v28, v28
	v_add_f32_e32 v35, v35, v36
	v_add_f32_e32 v34, v34, v35
	s_waitcnt vmcnt(8)
	v_mul_f32_e32 v35, v23, v23
	v_mul_f32_e32 v36, v25, v25
	v_fmac_f32_e32 v35, v22, v22
	v_fmac_f32_e32 v36, v24, v24
	v_add_f32_e32 v35, v35, v36
	v_add_f32_e32 v34, v34, v35
	v_mul_f32_e32 v35, v19, v19
	v_mul_f32_e32 v36, v21, v21
	v_fmac_f32_e32 v35, v18, v18
	v_fmac_f32_e32 v36, v20, v20
	v_add_f32_e32 v35, v35, v36
	v_add_f32_e32 v34, v34, v35
	s_waitcnt vmcnt(6)
	v_mul_f32_e32 v35, v15, v15
	v_mul_f32_e32 v36, v17, v17
	v_fmac_f32_e32 v35, v14, v14
	v_fmac_f32_e32 v36, v16, v16
	v_add_f32_e32 v35, v35, v36
	v_add_f32_e32 v34, v34, v35
	v_mul_f32_e32 v35, v11, v11
	v_mul_f32_e32 v36, v13, v13
	v_fmac_f32_e32 v35, v10, v10
	v_fmac_f32_e32 v36, v12, v12
	v_add_f32_e32 v35, v35, v36
	v_add_f32_e32 v34, v34, v35
	s_waitcnt vmcnt(4)
	v_mul_f32_e32 v35, v7, v7
	v_mul_f32_e32 v36, v9, v9
	v_fmac_f32_e32 v35, v6, v6
	v_fmac_f32_e32 v36, v8, v8
	v_add_f32_e32 v35, v35, v36
	v_add_f32_e32 v34, v34, v35
	v_mul_f32_e32 v35, v3, v3
	v_mul_f32_e32 v36, v5, v5
	v_fmac_f32_e32 v35, v2, v2
	v_fmac_f32_e32 v36, v4, v4
	v_add_f32_e32 v35, v35, v36
	v_add_f32_e32 v34, v34, v35
	ds_bpermute_b32 v35, v70, v34
	s_ashr_i32 s11, s10, 31
	s_waitcnt lgkmcnt(0)
	v_add_f32_e32 v34, v34, v35
	ds_bpermute_b32 v35, v71, v34
	s_waitcnt lgkmcnt(0)
	v_add_f32_e32 v34, v34, v35
	ds_bpermute_b32 v35, v72, v34
	s_waitcnt lgkmcnt(0)
	v_add_f32_e32 v34, v34, v35
	ds_bpermute_b32 v35, v73, v34
	s_waitcnt lgkmcnt(0)
	v_add_f32_e32 v34, v34, v35
	ds_bpermute_b32 v35, v74, v34
	s_waitcnt lgkmcnt(0)
	v_add_f32_e32 v34, v34, v35
	ds_bpermute_b32 v35, v75, v34
	s_waitcnt lgkmcnt(0)
	v_add_f32_e32 v34, v34, v35
	v_fmamk_f32 v34, v34, 0x3a000000, v78
	v_mul_f32_e32 v35, 0x4f800000, v34
	v_cmp_gt_f32_e32 vcc, s18, v34
	s_nop 1
	v_cndmask_b32_e32 v34, v34, v35, vcc
	v_sqrt_f32_e32 v35, v34
	s_nop 0
	v_add_u32_e32 v36, -1, v35
	v_fma_f32 v37, -v36, v35, v34
	v_cmp_ge_f32_e64 s[6:7], 0, v37
	v_add_u32_e32 v37, 1, v35
	s_nop 0
	v_cndmask_b32_e64 v36, v35, v36, s[6:7]
	v_fma_f32 v35, -v37, v35, v34
	v_cmp_lt_f32_e64 s[6:7], 0, v35
	s_nop 1
	v_cndmask_b32_e64 v35, v36, v37, s[6:7]
	v_mul_f32_e32 v36, 0x37800000, v35
	v_cndmask_b32_e32 v35, v35, v36, vcc
	v_cmp_class_f32_e32 vcc, v34, v79
	s_nop 1
	v_cndmask_b32_e32 v34, v35, v34, vcc
	s_and_saveexec_b64 s[6:7], s[0:1]
	s_cbranch_execz .LBB0_333
	s_lshl_b64 s[14:15], s[10:11], 2
	s_add_u32 s14, s4, s14
	s_addc_u32 s15, s5, s15
	global_store_dword v67, v34, s[14:15]
	s_branch .LBB0_333
